# sg unit: the eight gating-weight row loads issued together after the barrier
# speedup vs baseline: 1.0023x; 1.0023x over previous
; __device__ __forceinline__ u32x4 pack8(f32x4 a, f32x4 b) { u32x4 w; w.x = cvt_pk_bf16(a[0], a[1]); w.y = cvt_pk_bf16(a[2], a[3]); w.z = cvt_pk_bf16(b[0], b[1]); w.w = cvt_pk_bf16(b[2], b[3]); return w; }
; __device__ __forceinline__ void unpack8(u32x4 w, f32x4& a, f32x4& b) { a = (f32x4){bf_lo(w.x), bf_hi(w.x), bf_lo(w.y), bf_hi(w.y)}; b = (f32x4){bf_lo(w.z), bf_hi(w.z), bf_lo(w.w), bf_hi(w.w)}; }
; #define LAS __attribute__((address_space(3)))
; __device__ __forceinline__ void sg_unit(LAS unsigned char* lds, const bf16_t* PROJ, bf16_t* YCAT, const float* lng, const float* lnb, const float* sgw, const float* sgb, int unit, int tid, int wave, int lane) {
;     ...
;     for (int rg = 0; rg < 2; ++rg) {
;         const int r = 64 * rg + lane; const float mean = st[2 * r], rstd = st[2 * r + 1];
; #pragma unroll
;         for (int cc = 0; cc < 2; ++cc) {
;             const int c16 = 2 * wave + cc;
;             f32x4 v0, v1; pg8::unpack8(*(const u32x4*)(zv + (size_t)r * INW + 8 * c16), v0, v1);
;             const f32x4 a0 = *(const f32x4*)(lng + g * 128 + 8 * c16), a1 = *(const f32x4*)(lng + g * 128 + 8 * c16 + 4);
;             const f32x4 b0 = *(const f32x4*)(lnb + g * 128 + 8 * c16), b1 = *(const f32x4*)(lnb + g * 128 + 8 * c16 + 4);
;             v0 = (v0 - mean) * rstd * a0 + b0; v1 = (v1 - mean) * rstd * a1 + b1;
;             LAS bf16_t* d = Zt + (8 * c16) * 136 + r;
;             d[0 * 136] = (bf16_t)f2bf(v0[0]); d[1 * 136] = (bf16_t)f2bf(v0[1]); d[2 * 136] = (bf16_t)f2bf(v0[2]); d[3 * 136] = (bf16_t)f2bf(v0[3]);
;             d[4 * 136] = (bf16_t)f2bf(v1[0]); d[5 * 136] = (bf16_t)f2bf(v1[1]); d[6 * 136] = (bf16_t)f2bf(v1[2]); d[7 * 136] = (bf16_t)f2bf(v1[3]);
;         }
;     }
;     __syncthreads();
;     const int fr = lane & 15, fq = lane >> 4, t = 16 * wave + fr, nks = (wave >> 1) + 1;
;     bf16x8 wf[4];
; #pragma unroll
;     for (int ks = 0; ks < 4; ++ks) {
;         u32x4 w = {0u, 0u, 0u, 0u};
;         if (ks < nks) {
;             const float* wp = sgw + ((size_t)(g * 128 + t)) * 128 + 32 * ks + 8 * fq;
;             f32x4 a0 = *(const f32x4*)wp, a1 = *(const f32x4*)(wp + 4);
;             const int s0 = 32 * ks + 8 * fq;
; #pragma unroll
;             for (int i = 0; i < 4; ++i) { if (s0 + i > t) a0[i] = 0.f; if (s0 + 4 + i > t) a1[i] = 0.f; }
;             w = pg8::pack8(a0, a1);
;         }
;         wf[ks] = as_bf8(w);
;     }
.LBB0_186:
	v_cndmask_b32_e64 v0, 0, 1, s[70:71]
	v_or_b32_e32 v45, s73, v166
	v_cmp_ne_u32_e32 vcc, 1, v0
	v_mul_u32_u24_e32 v0, 0x2400, v45
	v_lshl_add_u32 v47, v45, 3, 0
	v_lshl_add_u64 v[64:65], v[0:1], 1, s[68:69]
	ds_read_b64 v[68:69], v47 offset:34816
	global_load_dwordx4 v[60:63], v[64:65], off offset:16
	s_nop 0
	global_load_dwordx4 v[64:67], v[64:65], off
	v_mad_i32_i24 v45, v45, -6, v47
	s_mov_b32 s73, 64
	s_mov_b64 s[70:71], 0
	s_and_b64 vcc, exec, vcc
	s_waitcnt vmcnt(0)
	v_lshlrev_b32_e32 v0, 16, v64
	v_and_b32_e32 v47, 0xffff0000, v64
	v_lshlrev_b32_e32 v76, 16, v66
	v_and_b32_e32 v77, 0xffff0000, v66
	v_lshlrev_b32_e32 v74, 16, v67
	v_and_b32_e32 v75, 0xffff0000, v67
	s_waitcnt lgkmcnt(0)
	v_sub_f32_e32 v67, v47, v68
	v_sub_f32_e32 v66, v0, v68
	v_pk_mul_f32 v[66:67], v[68:69], v[66:67] op_sel:[1,0]
	v_lshlrev_b32_e32 v59, 16, v65
	v_pk_fma_f32 v[66:67], v[14:15], v[66:67], v[30:31]
	v_and_b32_e32 v64, 0xffff0000, v65
	v_bfe_u32 v47, v66, 16, 1
	v_sub_f32_e32 v65, v64, v68
	v_sub_f32_e32 v64, v59, v68
	v_add_u32_e32 v0, s92, v45
	v_add3_u32 v47, v66, v47, s80
	v_pk_mul_f32 v[64:65], v[68:69], v[64:65] op_sel:[1,0]
	ds_write_b16_d16_hi v0, v47
	v_bfe_u32 v47, v67, 16, 1
	v_pk_fma_f32 v[64:65], v[16:17], v[64:65], v[32:33]
	v_add3_u32 v47, v67, v47, s80
	ds_write_b16_d16_hi v0, v47 offset:272
	v_bfe_u32 v47, v64, 16, 1
	v_sub_f32_e32 v77, v77, v68
	v_sub_f32_e32 v76, v76, v68
	v_add3_u32 v47, v64, v47, s80
	v_pk_mul_f32 v[76:77], v[68:69], v[76:77] op_sel:[1,0]
	ds_write_b16_d16_hi v0, v47 offset:544
	v_bfe_u32 v47, v65, 16, 1
	v_pk_fma_f32 v[76:77], v[10:11], v[76:77], v[26:27]
	v_add3_u32 v47, v65, v47, s80
	ds_write_b16_d16_hi v0, v47 offset:816
	v_bfe_u32 v47, v76, 16, 1
	v_sub_f32_e32 v75, v75, v68
	v_sub_f32_e32 v74, v74, v68
	v_add3_u32 v47, v76, v47, s80
	v_pk_mul_f32 v[74:75], v[68:69], v[74:75] op_sel:[1,0]
	ds_write_b16_d16_hi v0, v47 offset:1088
	v_bfe_u32 v47, v77, 16, 1
	v_pk_fma_f32 v[74:75], v[12:13], v[74:75], v[28:29]
	v_add3_u32 v47, v77, v47, s80
	ds_write_b16_d16_hi v0, v47 offset:1360
	v_bfe_u32 v47, v74, 16, 1
	v_add3_u32 v47, v74, v47, s80
	ds_write_b16_d16_hi v0, v47 offset:1632
	v_bfe_u32 v47, v75, 16, 1
	v_add3_u32 v47, v75, v47, s80
	ds_write_b16_d16_hi v0, v47 offset:1904
	v_lshlrev_b32_e32 v0, 16, v60
	v_and_b32_e32 v47, 0xffff0000, v60
	v_lshlrev_b32_e32 v66, 16, v62
	v_and_b32_e32 v67, 0xffff0000, v62
	v_lshlrev_b32_e32 v64, 16, v63
	v_and_b32_e32 v65, 0xffff0000, v63
	v_sub_f32_e32 v63, v47, v68
	v_sub_f32_e32 v62, v0, v68
	v_pk_mul_f32 v[62:63], v[68:69], v[62:63] op_sel:[1,0]
	v_lshlrev_b32_e32 v59, 16, v61
	v_pk_fma_f32 v[62:63], v[6:7], v[62:63], v[22:23]
	v_and_b32_e32 v60, 0xffff0000, v61
	v_add_u32_e32 v0, s93, v45
	v_bfe_u32 v45, v62, 16, 1
	v_sub_f32_e32 v61, v60, v68
	v_sub_f32_e32 v60, v59, v68
	v_add3_u32 v45, v62, v45, s80
	v_pk_mul_f32 v[60:61], v[68:69], v[60:61] op_sel:[1,0]
	ds_write_b16_d16_hi v0, v45
	v_bfe_u32 v45, v63, 16, 1
	v_pk_fma_f32 v[60:61], v[8:9], v[60:61], v[24:25]
	v_add3_u32 v45, v63, v45, s80
	ds_write_b16_d16_hi v0, v45 offset:272
	v_bfe_u32 v45, v60, 16, 1
	v_sub_f32_e32 v67, v67, v68
	v_sub_f32_e32 v66, v66, v68
	v_add3_u32 v45, v60, v45, s80
	v_pk_mul_f32 v[66:67], v[68:69], v[66:67] op_sel:[1,0]
	ds_write_b16_d16_hi v0, v45 offset:544
	v_bfe_u32 v45, v61, 16, 1
	v_pk_fma_f32 v[66:67], v[2:3], v[66:67], v[18:19]
	v_add3_u32 v45, v61, v45, s80
	ds_write_b16_d16_hi v0, v45 offset:816
	v_bfe_u32 v45, v66, 16, 1
	v_sub_f32_e32 v65, v65, v68
	v_sub_f32_e32 v64, v64, v68
	v_add3_u32 v45, v66, v45, s80
	v_pk_mul_f32 v[64:65], v[68:69], v[64:65] op_sel:[1,0]
	ds_write_b16_d16_hi v0, v45 offset:1088
	v_bfe_u32 v45, v67, 16, 1
	v_pk_fma_f32 v[64:65], v[4:5], v[64:65], v[20:21]
	v_add3_u32 v45, v67, v45, s80
	ds_write_b16_d16_hi v0, v45 offset:1360
	v_bfe_u32 v45, v64, 16, 1
	v_add3_u32 v45, v64, v45, s80
	ds_write_b16_d16_hi v0, v45 offset:1632
	v_bfe_u32 v45, v65, 16, 1
	v_add3_u32 v45, v65, v45, s80
	ds_write_b16_d16_hi v0, v45 offset:1904
	s_cbranch_vccz .LBB0_186
	v_add_u32_e32 v0, s72, v73
	v_lshlrev_b64 v[2:3], 9, v[0:1]
	v_lshl_add_u64 v[14:15], v[42:43], 0, v[2:3]
	s_waitcnt lgkmcnt(0)
	s_barrier
	global_load_dwordx4 v[208:211], v[14:15], off offset:16
	global_load_dwordx4 v[212:215], v[14:15], off
	global_load_dwordx4 v[216:219], v[14:15], off offset:144
	global_load_dwordx4 v[220:223], v[14:15], off offset:128
	global_load_dwordx4 v[224:227], v[14:15], off offset:272
	global_load_dwordx4 v[228:231], v[14:15], off offset:256
	global_load_dwordx4 v[232:235], v[14:15], off offset:400
	global_load_dwordx4 v[236:239], v[14:15], off offset:384
	s_waitcnt vmcnt(0)
	v_mov_b32_e32 v2, v208
	v_mov_b32_e32 v3, v209
	v_mov_b32_e32 v4, v210
	v_mov_b32_e32 v5, v211
	v_mov_b32_e32 v6, v212
	v_mov_b32_e32 v7, v213
	v_mov_b32_e32 v8, v214
	v_mov_b32_e32 v9, v215
	v_mov_b32_e32 v10, s79
	v_readlane_b32 s68, v252, 43
	v_readlane_b32 s69, v252, 44
	s_and_b64 vcc, exec, s[68:69]
	s_nop 0
	v_cndmask_b32_e64 v4, v4, v4, s[4:5]
	s_nop 0
	v_cndmask_b32_e64 v11, v8, v8, s[74:75]
	v_cndmask_b32_e64 v12, v9, v9, s[74:75]
	v_cndmask_b32_e64 v13, v6, v10, s[74:75]
	v_cndmask_b32_e64 v10, v2, v10, s[4:5]
	v_cndmask_b32_e64 v2, v5, v5, s[4:5]
	v_cndmask_b32_e64 v3, v3, v3, s[4:5]
	v_cndmask_b32_e64 v5, v13, v6, s[6:7]
	v_cndmask_b32_e64 v6, v12, v9, s[6:7]
	v_cndmask_b32_e64 v8, v11, v8, s[6:7]
	v_cndmask_b32_e64 v9, v3, 0, s[8:9]
	v_cndmask_b32_e64 v3, v8, 0, s[10:11]
	v_cndmask_b32_e64 v8, v4, 0, s[12:13]
	v_cndmask_b32_e64 v4, v6, 0, s[14:15]
	v_cndmask_b32_e64 v7, 0, v7, s[6:7]
	v_cndmask_b32_e64 v6, v2, 0, s[16:17]
	v_cvt_pk_bf16_f32 v2, v5, v7
	v_cvt_pk_bf16_f32 v3, v3, v4
	v_cvt_pk_bf16_f32 v4, v10, v9
	v_cvt_pk_bf16_f32 v5, v8, v6
	s_cbranch_vccz .LBB0_189
	v_mov_b32_e32 v6, v216
	v_mov_b32_e32 v7, v217
	v_mov_b32_e32 v8, v218
	v_mov_b32_e32 v9, v219
	v_mov_b32_e32 v10, v220
	v_mov_b32_e32 v11, v221
	v_mov_b32_e32 v12, v222
	v_mov_b32_e32 v13, v223
	v_mov_b32_e32 v16, s79
	v_readlane_b32 s68, v255, 45
	v_readlane_b32 s69, v255, 46
	s_nop 0
	v_cndmask_b32_e64 v8, v8, v8, s[20:21]
	s_nop 0
	v_cndmask_b32_e64 v16, v10, v16, s[18:19]
	v_cndmask_b32_e64 v13, v13, v13, s[18:19]
	v_cndmask_b32_e64 v12, v12, v12, s[18:19]
	v_cndmask_b32_e64 v11, v11, v11, s[18:19]
	v_mov_b32_e32 v10, s79
	v_cndmask_b32_e64 v7, v7, v7, s[20:21]
	v_cndmask_b32_e64 v10, v6, v10, s[20:21]
	v_cndmask_b32_e64 v6, v9, v9, s[20:21]
	v_cndmask_b32_e64 v9, v11, 0, s[68:69]
	v_cndmask_b32_e64 v11, v7, 0, s[24:25]
	v_cndmask_b32_e64 v7, v12, 0, s[26:27]
	v_cndmask_b32_e64 v12, v8, 0, s[28:29]
	v_cndmask_b32_e64 v8, v13, 0, s[30:31]
	v_cndmask_b32_e64 v13, v6, 0, s[34:35]
	v_cvt_pk_bf16_f32 v6, v16, v9
	v_cvt_pk_bf16_f32 v7, v7, v8
	v_cvt_pk_bf16_f32 v8, v10, v11
	v_cvt_pk_bf16_f32 v9, v12, v13
	s_branch .LBB0_190

; __device__ __forceinline__ u32x4 pack8(f32x4 a, f32x4 b) { u32x4 w; w.x = cvt_pk_bf16(a[0], a[1]); w.y = cvt_pk_bf16(a[2], a[3]); w.z = cvt_pk_bf16(b[0], b[1]); w.w = cvt_pk_bf16(b[2], b[3]); return w; }
; __device__ __forceinline__ void sg_unit(LAS unsigned char* lds, const bf16_t* PROJ, bf16_t* YCAT, const float* lng, const float* lnb, const float* sgw, const float* sgb, int unit, int tid, int wave, int lane) {
;     ...
;     for (int ks = 0; ks < 4; ++ks) {
;         u32x4 w = {0u, 0u, 0u, 0u};
;         if (ks < nks) {
;             const float* wp = sgw + ((size_t)(g * 128 + t)) * 128 + 32 * ks + 8 * fq;
;             f32x4 a0 = *(const f32x4*)wp, a1 = *(const f32x4*)(wp + 4);
;             const int s0 = 32 * ks + 8 * fq;
; #pragma unroll
;             for (int i = 0; i < 4; ++i) { if (s0 + i > t) a0[i] = 0.f; if (s0 + 4 + i > t) a1[i] = 0.f; }
;             w = pg8::pack8(a0, a1);
;         }
;         wf[ks] = as_bf8(w);
.LBB0_190:
	v_readlane_b32 s70, v252, 38
	v_readlane_b32 s71, v252, 39
	s_andn2_b64 vcc, exec, s[70:71]
	s_nop 0
	v_cndmask_b32_e64 v10, 0, 1, s[70:71]
	v_cmp_ne_u32_e64 s[68:69], 1, v10
	s_cbranch_vccnz .LBB0_192
	v_mov_b32_e32 v10, v224
	v_mov_b32_e32 v11, v225
	v_mov_b32_e32 v12, v226
	v_mov_b32_e32 v13, v227
	v_mov_b32_e32 v16, v228
	v_mov_b32_e32 v17, v229
	v_mov_b32_e32 v18, v230
	v_mov_b32_e32 v19, v231
	v_mov_b32_e32 v20, s79
	s_nop 0
	v_cndmask_b32_e64 v12, v12, v12, s[38:39]
	s_nop 0
	v_cndmask_b32_e64 v20, v16, v20, s[36:37]
	v_cndmask_b32_e64 v19, v19, v19, s[36:37]
	v_cndmask_b32_e64 v18, v18, v18, s[36:37]
	v_cndmask_b32_e64 v17, v17, v17, s[36:37]
	v_mov_b32_e32 v16, s79
	v_cndmask_b32_e64 v11, v11, v11, s[38:39]
	v_cndmask_b32_e64 v16, v10, v16, s[38:39]
	v_cndmask_b32_e64 v10, v13, v13, s[38:39]
	v_cndmask_b32_e64 v13, v17, 0, s[40:41]
	v_cndmask_b32_e64 v17, v11, 0, s[42:43]
	v_cndmask_b32_e64 v11, v18, 0, s[44:45]
	v_cndmask_b32_e64 v18, v12, 0, s[46:47]
	v_cndmask_b32_e64 v12, v19, 0, s[48:49]
	v_cndmask_b32_e64 v19, v10, 0, s[50:51]
	v_cvt_pk_bf16_f32 v10, v20, v13
	v_cvt_pk_bf16_f32 v11, v11, v12
	v_cvt_pk_bf16_f32 v12, v16, v17
	v_cvt_pk_bf16_f32 v13, v18, v19
	s_branch .LBB0_193

; __device__ __forceinline__ u32x4 pack8(f32x4 a, f32x4 b) { u32x4 w; w.x = cvt_pk_bf16(a[0], a[1]); w.y = cvt_pk_bf16(a[2], a[3]); w.z = cvt_pk_bf16(b[0], b[1]); w.w = cvt_pk_bf16(b[2], b[3]); return w; }
; __device__ __forceinline__ void sg_unit(LAS unsigned char* lds, const bf16_t* PROJ, bf16_t* YCAT, const float* lng, const float* lnb, const float* sgw, const float* sgb, int unit, int tid, int wave, int lane) {
;     ...
;     for (int ks = 0; ks < 4; ++ks) {
;         u32x4 w = {0u, 0u, 0u, 0u};
;         if (ks < nks) {
;             const float* wp = sgw + ((size_t)(g * 128 + t)) * 128 + 32 * ks + 8 * fq;
;             f32x4 a0 = *(const f32x4*)wp, a1 = *(const f32x4*)(wp + 4);
;             const int s0 = 32 * ks + 8 * fq;
; #pragma unroll
;             for (int i = 0; i < 4; ++i) { if (s0 + i > t) a0[i] = 0.f; if (s0 + 4 + i > t) a1[i] = 0.f; }
;             w = pg8::pack8(a0, a1);
;         }
;         wf[ks] = as_bf8(w);
.LBB0_193:
	v_readlane_b32 s72, v252, 34
	v_readlane_b32 s73, v252, 35
	s_andn2_b64 vcc, exec, s[72:73]
	s_nop 0
	v_cndmask_b32_e64 v16, 0, 1, s[72:73]
	v_cmp_ne_u32_e64 s[70:71], 1, v16
	s_cbranch_vccnz .LBB0_195
	v_mov_b32_e32 v16, v232
	v_mov_b32_e32 v17, v233
	v_mov_b32_e32 v18, v234
	v_mov_b32_e32 v19, v235
	v_mov_b32_e32 v20, v236
	v_mov_b32_e32 v21, v237
	v_mov_b32_e32 v22, v238
	v_mov_b32_e32 v23, v239
	v_mov_b32_e32 v14, s79
	s_nop 0
	v_cndmask_b32_e64 v17, v17, v17, s[54:55]
	s_nop 0
	v_cndmask_b32_e64 v15, v20, v14, s[52:53]
	v_cndmask_b32_e64 v20, v23, v23, s[52:53]
	v_cndmask_b32_e64 v22, v22, v22, s[52:53]
	v_cndmask_b32_e64 v21, v21, v21, s[52:53]
	v_cndmask_b32_e64 v16, v16, v14, s[54:55]
	v_cndmask_b32_e64 v14, v19, v19, s[54:55]
	v_cndmask_b32_e64 v18, v18, v18, s[54:55]
	v_cndmask_b32_e64 v17, v17, 0, s[58:59]
	v_cndmask_b32_e64 v19, v21, 0, s[56:57]
	v_cndmask_b32_e64 v21, v22, 0, s[60:61]
	v_cndmask_b32_e64 v18, v18, 0, s[62:63]
	v_cndmask_b32_e64 v20, v20, 0, s[64:65]
	v_cndmask_b32_e64 v22, v14, 0, s[66:67]
	v_cvt_pk_bf16_f32 v14, v15, v19
	v_cvt_pk_bf16_f32 v15, v21, v20
	v_cvt_pk_bf16_f32 v16, v16, v17
	v_cvt_pk_bf16_f32 v17, v18, v22
	s_branch .LBB0_196
